# Hyena: batch the serialized H3-row loads of the filter-generation loop and replace the serialized Z-init conv loop with a batched hand-written one
# speedup vs baseline: 1.0511x; 1.0124x over previous
.LBB0_297:
	s_add_i32 s0, s46, 0x400
	s_ashr_i32 s1, s0, 31
	s_lshl_b64 s[52:53], s[0:1], 2
	s_add_u32 s34, s72, s52
	s_addc_u32 s35, s73, s53
	s_ashr_i32 s47, s46, 31
	s_barrier
	global_load_dword v142, v87, s[34:35]
	s_lshl_b64 s[34:35], s[46:47], 2
	s_add_u32 s34, s72, s34
	s_addc_u32 s35, s73, s35
	s_add_u32 s52, s74, s52
	s_addc_u32 s53, s75, s53
	global_load_dword v139, v195, s[34:35] offset:2048
	global_load_dword v138, v196, s[34:35]
	global_load_dword v143, v87, s[52:53]
	s_lshl_b64 s[0:1], s[0:1], 15
	s_add_u32 s0, s38, s0
	s_addc_u32 s1, s39, s1
	v_lshlrev_b32_e32 v202, 2, v82
	v_mov_b32_e32 v86, v224
	v_mov_b32_e32 v144, v164
	v_lshlrev_b32_e32 v86, 4, v164
	v_add_u32_e32 v246, 0x2000, v86
	v_add_u32_e32 v247, 0x4000, v86
	v_add_u32_e32 v248, 0x6000, v86
	global_load_dwordx4 v[204:207], v86, s[0:1]
	global_load_dwordx4 v[226:229], v246, s[0:1]
	global_load_dwordx4 v[230:233], v247, s[0:1]
	global_load_dwordx4 v[234:237], v248, s[0:1]
	global_load_ushort v238, v86, s[0:1] offset:-2
	global_load_ushort v239, v246, s[0:1] offset:-2
	global_load_ushort v240, v247, s[0:1] offset:-2
	global_load_ushort v241, v248, s[0:1] offset:-2
	global_load_ushort v242, v86, s[0:1] offset:16
	global_load_ushort v243, v246, s[0:1] offset:16
	global_load_ushort v244, v247, s[0:1] offset:16
	global_load_ushort v245, v248, s[0:1] offset:16
	v_lshlrev_b32_e32 v249, 5, v164
	v_add_u32_e32 v249, 0x10000, v249
	s_movk_i32 s47, 0x1ff
	v_cmp_ne_u32_e64 s[52:53], 0, v164
	v_cmp_ne_u32_e64 s[54:55], s47, v164
	s_waitcnt vmcnt(0)
	v_lshlrev_b32_e32 v140, 16, v204
	v_and_b32_e32 v141, 0xffff0000, v204
	v_lshlrev_b32_e32 v144, 16, v205
	v_and_b32_e32 v145, 0xffff0000, v205
	v_lshlrev_b32_e32 v146, 16, v206
	v_and_b32_e32 v147, 0xffff0000, v206
	v_lshlrev_b32_e32 v148, 16, v207
	v_and_b32_e32 v208, 0xffff0000, v207
	v_lshlrev_b32_e32 v238, 16, v238
	v_lshlrev_b32_e32 v242, 16, v242
	v_cndmask_b32_e64 v238, 0, v238, s[52:53]
	v_cndmask_b32_e64 v242, 0, v242, s[54:55]
	v_mul_f32_e32 v209, v139, v140
	v_mul_f32_e32 v86, v138, v141
	v_fma_f32 v209, v142, v238, v209
	v_add_f32_e32 v209, v86, v209
	v_add_f32_e32 v204, v143, v209
	v_mul_f32_e32 v209, v139, v141
	v_mul_f32_e32 v86, v138, v144
	v_fma_f32 v209, v142, v140, v209
	v_add_f32_e32 v209, v86, v209
	v_add_f32_e32 v205, v143, v209
	v_mul_f32_e32 v209, v139, v144
	v_mul_f32_e32 v86, v138, v145
	v_fma_f32 v209, v142, v141, v209
	v_add_f32_e32 v209, v86, v209
	v_add_f32_e32 v206, v143, v209
	v_mul_f32_e32 v209, v139, v145
	v_mul_f32_e32 v86, v138, v146
	v_fma_f32 v209, v142, v144, v209
	v_add_f32_e32 v209, v86, v209
	v_add_f32_e32 v207, v143, v209
	v_mul_f32_e32 v209, v139, v146
	v_mul_f32_e32 v86, v138, v147
	v_fma_f32 v209, v142, v145, v209
	v_add_f32_e32 v209, v86, v209
	v_add_f32_e32 v250, v143, v209
	v_mul_f32_e32 v209, v139, v147
	v_mul_f32_e32 v86, v138, v148
	v_fma_f32 v209, v142, v146, v209
	v_add_f32_e32 v209, v86, v209
	v_add_f32_e32 v251, v143, v209
	v_mul_f32_e32 v209, v139, v148
	v_mul_f32_e32 v86, v138, v208
	v_fma_f32 v209, v142, v147, v209
	v_add_f32_e32 v209, v86, v209
	v_add_f32_e32 v252, v143, v209
	v_mul_f32_e32 v209, v139, v208
	v_mul_f32_e32 v86, v138, v242
	v_fma_f32 v209, v142, v148, v209
	v_add_f32_e32 v209, v86, v209
	v_add_f32_e32 v253, v143, v209
	ds_write_b128 v249, v[204:207] offset:0
	ds_write_b128 v249, v[250:253] offset:16
	v_lshlrev_b32_e32 v140, 16, v226
	v_and_b32_e32 v141, 0xffff0000, v226
	v_lshlrev_b32_e32 v144, 16, v227
	v_and_b32_e32 v145, 0xffff0000, v227
	v_lshlrev_b32_e32 v146, 16, v228
	v_and_b32_e32 v147, 0xffff0000, v228
	v_lshlrev_b32_e32 v148, 16, v229
	v_and_b32_e32 v208, 0xffff0000, v229
	v_lshlrev_b32_e32 v239, 16, v239
	v_lshlrev_b32_e32 v243, 16, v243
	v_cndmask_b32_e64 v239, 0, v239, s[52:53]
	v_cndmask_b32_e64 v243, 0, v243, s[54:55]
	v_mul_f32_e32 v209, v139, v140
	v_mul_f32_e32 v86, v138, v141
	v_fma_f32 v209, v142, v239, v209
	v_add_f32_e32 v209, v86, v209
	v_add_f32_e32 v226, v143, v209
	v_mul_f32_e32 v209, v139, v141
	v_mul_f32_e32 v86, v138, v144
	v_fma_f32 v209, v142, v140, v209
	v_add_f32_e32 v209, v86, v209
	v_add_f32_e32 v227, v143, v209
	v_mul_f32_e32 v209, v139, v144
	v_mul_f32_e32 v86, v138, v145
	v_fma_f32 v209, v142, v141, v209
	v_add_f32_e32 v209, v86, v209
	v_add_f32_e32 v228, v143, v209
	v_mul_f32_e32 v209, v139, v145
	v_mul_f32_e32 v86, v138, v146
	v_fma_f32 v209, v142, v144, v209
	v_add_f32_e32 v209, v86, v209
	v_add_f32_e32 v229, v143, v209
	v_mul_f32_e32 v209, v139, v146
	v_mul_f32_e32 v86, v138, v147
	v_fma_f32 v209, v142, v145, v209
	v_add_f32_e32 v209, v86, v209
	v_add_f32_e32 v250, v143, v209
	v_mul_f32_e32 v209, v139, v147
	v_mul_f32_e32 v86, v138, v148
	v_fma_f32 v209, v142, v146, v209
	v_add_f32_e32 v209, v86, v209
	v_add_f32_e32 v251, v143, v209
	v_mul_f32_e32 v209, v139, v148
	v_mul_f32_e32 v86, v138, v208
	v_fma_f32 v209, v142, v147, v209
	v_add_f32_e32 v209, v86, v209
	v_add_f32_e32 v252, v143, v209
	v_mul_f32_e32 v209, v139, v208
	v_mul_f32_e32 v86, v138, v243
	v_fma_f32 v209, v142, v148, v209
	v_add_f32_e32 v209, v86, v209
	v_add_f32_e32 v253, v143, v209
	ds_write_b128 v249, v[226:229] offset:16384
	ds_write_b128 v249, v[250:253] offset:16400
	v_lshlrev_b32_e32 v140, 16, v230
	v_and_b32_e32 v141, 0xffff0000, v230
	v_lshlrev_b32_e32 v144, 16, v231
	v_and_b32_e32 v145, 0xffff0000, v231
	v_lshlrev_b32_e32 v146, 16, v232
	v_and_b32_e32 v147, 0xffff0000, v232
	v_lshlrev_b32_e32 v148, 16, v233
	v_and_b32_e32 v208, 0xffff0000, v233
	v_lshlrev_b32_e32 v240, 16, v240
	v_lshlrev_b32_e32 v244, 16, v244
	v_cndmask_b32_e64 v240, 0, v240, s[52:53]
	v_cndmask_b32_e64 v244, 0, v244, s[54:55]
	v_mul_f32_e32 v209, v139, v140
	v_mul_f32_e32 v86, v138, v141
	v_fma_f32 v209, v142, v240, v209
	v_add_f32_e32 v209, v86, v209
	v_add_f32_e32 v230, v143, v209
	v_mul_f32_e32 v209, v139, v141
	v_mul_f32_e32 v86, v138, v144
	v_fma_f32 v209, v142, v140, v209
	v_add_f32_e32 v209, v86, v209
	v_add_f32_e32 v231, v143, v209
	v_mul_f32_e32 v209, v139, v144
	v_mul_f32_e32 v86, v138, v145
	v_fma_f32 v209, v142, v141, v209
	v_add_f32_e32 v209, v86, v209
	v_add_f32_e32 v232, v143, v209
	v_mul_f32_e32 v209, v139, v145
	v_mul_f32_e32 v86, v138, v146
	v_fma_f32 v209, v142, v144, v209
	v_add_f32_e32 v209, v86, v209
	v_add_f32_e32 v233, v143, v209
	v_mul_f32_e32 v209, v139, v146
	v_mul_f32_e32 v86, v138, v147
	v_fma_f32 v209, v142, v145, v209
	v_add_f32_e32 v209, v86, v209
	v_add_f32_e32 v250, v143, v209
	v_mul_f32_e32 v209, v139, v147
	v_mul_f32_e32 v86, v138, v148
	v_fma_f32 v209, v142, v146, v209
	v_add_f32_e32 v209, v86, v209
	v_add_f32_e32 v251, v143, v209
	v_mul_f32_e32 v209, v139, v148
	v_mul_f32_e32 v86, v138, v208
	v_fma_f32 v209, v142, v147, v209
	v_add_f32_e32 v209, v86, v209
	v_add_f32_e32 v252, v143, v209
	v_mul_f32_e32 v209, v139, v208
	v_mul_f32_e32 v86, v138, v244
	v_fma_f32 v209, v142, v148, v209
	v_add_f32_e32 v209, v86, v209
	v_add_f32_e32 v253, v143, v209
	ds_write_b128 v249, v[230:233] offset:32768
	ds_write_b128 v249, v[250:253] offset:32784
	v_lshlrev_b32_e32 v140, 16, v234
	v_and_b32_e32 v141, 0xffff0000, v234
	v_lshlrev_b32_e32 v144, 16, v235
	v_and_b32_e32 v145, 0xffff0000, v235
	v_lshlrev_b32_e32 v146, 16, v236
	v_and_b32_e32 v147, 0xffff0000, v236
	v_lshlrev_b32_e32 v148, 16, v237
	v_and_b32_e32 v208, 0xffff0000, v237
	v_lshlrev_b32_e32 v241, 16, v241
	v_lshlrev_b32_e32 v245, 16, v245
	v_cndmask_b32_e64 v241, 0, v241, s[52:53]
	v_cndmask_b32_e64 v245, 0, v245, s[54:55]
	v_mul_f32_e32 v209, v139, v140
	v_mul_f32_e32 v86, v138, v141
	v_fma_f32 v209, v142, v241, v209
	v_add_f32_e32 v209, v86, v209
	v_add_f32_e32 v234, v143, v209
	v_mul_f32_e32 v209, v139, v141
	v_mul_f32_e32 v86, v138, v144
	v_fma_f32 v209, v142, v140, v209
	v_add_f32_e32 v209, v86, v209
	v_add_f32_e32 v235, v143, v209
	v_mul_f32_e32 v209, v139, v144
	v_mul_f32_e32 v86, v138, v145
	v_fma_f32 v209, v142, v141, v209
	v_add_f32_e32 v209, v86, v209
	v_add_f32_e32 v236, v143, v209
	v_mul_f32_e32 v209, v139, v145
	v_mul_f32_e32 v86, v138, v146
	v_fma_f32 v209, v142, v144, v209
	v_add_f32_e32 v209, v86, v209
	v_add_f32_e32 v237, v143, v209
	v_mul_f32_e32 v209, v139, v146
	v_mul_f32_e32 v86, v138, v147
	v_fma_f32 v209, v142, v145, v209
	v_add_f32_e32 v209, v86, v209
	v_add_f32_e32 v250, v143, v209
	v_mul_f32_e32 v209, v139, v147
	v_mul_f32_e32 v86, v138, v148
	v_fma_f32 v209, v142, v146, v209
	v_add_f32_e32 v209, v86, v209
	v_add_f32_e32 v251, v143, v209
	v_mul_f32_e32 v209, v139, v148
	v_mul_f32_e32 v86, v138, v208
	v_fma_f32 v209, v142, v147, v209
	v_add_f32_e32 v209, v86, v209
	v_add_f32_e32 v252, v143, v209
	v_mul_f32_e32 v209, v139, v208
	v_mul_f32_e32 v86, v138, v245
	v_fma_f32 v209, v142, v148, v209
	v_add_f32_e32 v209, v86, v209
	v_add_f32_e32 v253, v143, v209
	ds_write_b128 v249, v[234:237] offset:49152
	ds_write_b128 v249, v[250:253] offset:49168
	s_and_saveexec_b64 s[0:1], s[6:7]
	s_cbranch_execz .LBB0_307
	v_add_u32_e32 v138, s46, v83
	v_ashrrev_i32_e32 v139, 31, v138
	v_lshl_add_u64 v[138:139], v[138:139], 2, s[40:41]
	global_load_dword v86, v[138:139], off
	s_waitcnt vmcnt(0)
	ds_write_b32 v160, v86

.LBB0_310:
	global_load_dwordx4 v[204:207], v[154:155], off
	v_add_co_u32_e32 v246, vcc, 0x20000, v154
	s_nop 1
	v_addc_co_u32_e32 v247, vcc, 0, v155, vcc
	v_add_co_u32_e32 v248, vcc, 0x40000, v154
	s_nop 1
	v_addc_co_u32_e32 v249, vcc, 0, v155, vcc
	v_add_co_u32_e32 v250, vcc, 0x60000, v154
	s_nop 1
	v_addc_co_u32_e32 v251, vcc, 0, v155, vcc
	v_mov_b32_e32 v86, s52
	ds_read_b128 v[226:229], v86
	ds_read_b128 v[230:233], v86 offset:256
	s_mov_b32 s53, 0x20000
	s_add_i32 s50, s50, 4
	s_add_i32 s52, s52, 16
	s_waitcnt lgkmcnt(1)
	v_mov_b32_e32 v157, v227
	s_waitcnt lgkmcnt(0)
	v_mov_b32_e32 v156, v230
	v_mov_b32_e32 v242, v232
	v_mov_b32_e32 v243, v229
	v_mov_b32_e32 v227, v231
	v_mov_b32_e32 v229, v233
	global_load_dwordx4 v[230:233], v[246:247], off
	global_load_dwordx4 v[234:237], v[248:249], off
	global_load_dwordx4 v[238:241], v[250:251], off
	s_cmp_lt_u32 s50, 60
	s_waitcnt vmcnt(3)
	v_pk_mul_f32 v[208:209], v[204:205], v[156:157]
	v_pk_mul_f32 v[252:253], v[206:207], v[242:243]
	v_pk_fma_f32 v[208:209], v[204:205], v[226:227], v[208:209] op_sel:[0,0,1] op_sel_hi:[1,1,0]
	v_pk_fma_f32 v[252:253], v[206:207], v[228:229], v[252:253] op_sel:[0,0,1] op_sel_hi:[1,1,0]
	s_nop 0
	v_pk_add_f32 v[208:209], v[208:209], v[252:253]
	s_nop 0
	v_pk_add_f32 v[150:151], v[150:151], v[208:209]
	s_waitcnt vmcnt(2)
	v_pk_mul_f32 v[208:209], v[230:231], v[156:157]
	v_pk_mul_f32 v[252:253], v[232:233], v[242:243]
	v_pk_fma_f32 v[208:209], v[230:231], v[226:227], v[208:209] op_sel:[0,0,1] op_sel_hi:[1,1,0]
	v_pk_fma_f32 v[252:253], v[232:233], v[228:229], v[252:253] op_sel:[0,0,1] op_sel_hi:[1,1,0]
	s_nop 0
	v_pk_add_f32 v[208:209], v[208:209], v[252:253]
	s_nop 0
	v_pk_add_f32 v[146:147], v[146:147], v[208:209]
	s_waitcnt vmcnt(1)
	v_pk_mul_f32 v[208:209], v[234:235], v[156:157]
	v_pk_mul_f32 v[252:253], v[236:237], v[242:243]
	v_pk_fma_f32 v[208:209], v[234:235], v[226:227], v[208:209] op_sel:[0,0,1] op_sel_hi:[1,1,0]
	v_pk_fma_f32 v[252:253], v[236:237], v[228:229], v[252:253] op_sel:[0,0,1] op_sel_hi:[1,1,0]
	s_nop 0
	v_pk_add_f32 v[208:209], v[208:209], v[252:253]
	s_nop 0
	v_pk_add_f32 v[142:143], v[142:143], v[208:209]
	v_lshl_add_u64 v[154:155], v[154:155], 0, 16
	s_waitcnt vmcnt(0)
	v_pk_mul_f32 v[156:157], v[238:239], v[156:157]
	v_pk_mul_f32 v[208:209], v[240:241], v[242:243]
	v_pk_fma_f32 v[156:157], v[238:239], v[226:227], v[156:157] op_sel:[0,0,1] op_sel_hi:[1,1,0]
	v_pk_fma_f32 v[208:209], v[240:241], v[228:229], v[208:209] op_sel:[0,0,1] op_sel_hi:[1,1,0]
	ds_read_b128 v[226:229], v86 offset:512
	ds_read_b128 v[242:245], v86 offset:768
	v_pk_add_f32 v[156:157], v[156:157], v[208:209]
	s_nop 0
	v_pk_add_f32 v[138:139], v[138:139], v[156:157]
	s_waitcnt lgkmcnt(1)
	v_mov_b32_e32 v157, v227
	s_waitcnt lgkmcnt(0)
	v_mov_b32_e32 v156, v242
	v_pk_mul_f32 v[208:209], v[204:205], v[156:157]
	v_mov_b32_e32 v227, v243
	v_pk_fma_f32 v[204:205], v[204:205], v[226:227], v[208:209] op_sel:[0,0,1] op_sel_hi:[1,1,0]
	v_mov_b32_e32 v208, v244
	v_mov_b32_e32 v209, v229
	v_pk_mul_f32 v[242:243], v[206:207], v[208:209]
	v_mov_b32_e32 v229, v245
	v_pk_fma_f32 v[206:207], v[206:207], v[228:229], v[242:243] op_sel:[0,0,1] op_sel_hi:[1,1,0]
	s_nop 0
	v_pk_add_f32 v[204:205], v[204:205], v[206:207]
	v_pk_mul_f32 v[206:207], v[232:233], v[208:209]
	v_pk_add_f32 v[152:153], v[152:153], v[204:205]
	v_pk_mul_f32 v[204:205], v[230:231], v[156:157]
	v_pk_fma_f32 v[206:207], v[232:233], v[228:229], v[206:207] op_sel:[0,0,1] op_sel_hi:[1,1,0]
	v_pk_fma_f32 v[204:205], v[230:231], v[226:227], v[204:205] op_sel:[0,0,1] op_sel_hi:[1,1,0]
	s_nop 0
	v_pk_add_f32 v[204:205], v[204:205], v[206:207]
	v_pk_mul_f32 v[206:207], v[236:237], v[208:209]
	v_pk_add_f32 v[148:149], v[148:149], v[204:205]
	v_pk_mul_f32 v[204:205], v[234:235], v[156:157]
	v_pk_fma_f32 v[206:207], v[236:237], v[228:229], v[206:207] op_sel:[0,0,1] op_sel_hi:[1,1,0]
	v_pk_fma_f32 v[204:205], v[234:235], v[226:227], v[204:205] op_sel:[0,0,1] op_sel_hi:[1,1,0]
	v_pk_mul_f32 v[156:157], v[238:239], v[156:157]
	v_pk_add_f32 v[204:205], v[204:205], v[206:207]
	v_pk_fma_f32 v[156:157], v[238:239], v[226:227], v[156:157] op_sel:[0,0,1] op_sel_hi:[1,1,0]
	v_pk_add_f32 v[144:145], v[144:145], v[204:205]
	v_pk_mul_f32 v[204:205], v[240:241], v[208:209]
	s_nop 0
	v_pk_fma_f32 v[204:205], v[240:241], v[228:229], v[204:205] op_sel:[0,0,1] op_sel_hi:[1,1,0]
	s_nop 0
	v_pk_add_f32 v[156:157], v[156:157], v[204:205]
	s_nop 0
	v_pk_add_f32 v[140:141], v[140:141], v[156:157]
	s_cbranch_scc1 .LBB0_310
	v_or_b32_e32 v154, s47, v164
	v_cvt_f32_u32_e32 v86, v154
	v_div_scale_f32 v155, s[52:53], s57, s57, v86
	v_rcp_f32_e32 v156, v155
	v_div_scale_f32 v157, vcc, v86, s57, v86
	v_fma_f32 v204, -v155, v156, 1.0
	v_fmac_f32_e32 v156, v204, v156
	v_mul_f32_e32 v204, v157, v156
	v_fma_f32 v205, -v155, v204, v157
	v_fmac_f32_e32 v204, v205, v156
	v_fma_f32 v155, -v155, v204, v157
	v_div_fmas_f32 v155, v155, v156, v204
	v_div_fixup_f32 v86, v155, s57, v86
	v_mul_f32_e64 v86, |v203|, v86
	v_mul_f32_e32 v155, 0x3fb8aa3b, v86
	v_fma_f32 v156, v86, s58, -v155
	v_rndne_f32_e32 v157, v155
	v_fmac_f32_e32 v156, 0x32a5705f, v86
	v_sub_f32_e32 v155, v155, v157
	v_add_f32_e32 v155, v155, v156
	v_cvt_i32_f32_e32 v156, v157
	v_exp_f32_e32 v155, v155
	v_cmp_ngt_f32_e32 vcc, s59, v86
	v_ldexp_f32 v155, v155, v156
	s_nop 0
	v_cndmask_b32_e32 v155, 0, v155, vcc
	v_cmp_nlt_f32_e32 vcc, s60, v86
	s_nop 1
	v_cndmask_b32_e32 v155, v200, v155, vcc
	v_mul_f32_e32 v86, v155, v150
	v_mul_f32_e32 v156, v155, v151
	v_mul_f32_e32 v152, v155, v152
	v_mul_f32_e32 v153, v155, v153
	v_cmp_ne_u32_e32 vcc, 0, v154
	s_and_saveexec_b64 s[52:53], vcc
	s_xor_b64 s[52:53], exec, s[52:53]
	s_cbranch_execz .LBB0_313
	v_lshl_add_u32 v150, v154, 3, 0
	ds_write_b64 v150, v[86:87]
	v_sub_u32_e32 v86, 0x2000, v154
	v_mov_b32_e32 v155, v87
	v_lshl_add_u32 v150, v86, 3, 0
	v_mov_b32_e32 v157, v87
	ds_write_b64 v150, v[156:157]
	v_lshl_add_u64 v[150:151], v[154:155], 2, s[80:81]
	v_lshlrev_b32_e32 v86, 2, v86
	global_store_dword v[150:151], v152, off
	global_store_dword v86, v153, s[80:81]
	v_mov_b64_e32 v[150:151], v[154:155]
